# attention item prologue: four Q staging loads issued together instead of load-wait-write x4
# baseline (speedup 1.0000x reference)
.LBB0_1095:
	s_add_i32 s1, s50, 0xfffffa00
	s_and_b32 s4, s50, 0x7f
	v_mov_b32_e32 v12, v179
	s_and_b32 s0, s50, 0x7f0
	s_lshr_b32 s1, s1, 1
	s_lshr_b32 s2, s36, 7
	s_and_b32 s3, s50, 1
	s_add_i32 s4, s4, 2
	s_cmpk_eq_i32 s0, 0x600
	v_lshrrev_b32_e32 v0, 4, v12
	v_xor_b32_e32 v0, v0, v12
	s_cselect_b32 s20, s1, s2
	s_cselect_b32 s5, s3, s4
	v_lshlrev_b32_e32 v0, 3, v0
	s_cselect_b32 s21, 4, 0x104
	s_lshl_b32 s8, s20, 1
	s_lshl_b32 s44, s5, 7
	s_waitcnt vmcnt(4)
	v_and_b32_e32 v15, 56, v0
	v_lshrrev_b32_e32 v0, 3, v12
	s_movk_i32 s5, 0x4100
	v_lshlrev_b32_e32 v17, 4, v12
	v_readlane_b32 s6, v251, 58
	v_ashrrev_i32_e32 v10, 10, v12
	v_mul_lo_u32 v16, v0, s5
	v_and_b32_e32 v0, 0x70, v17
	v_readlane_b32 s7, v251, 59
	v_add_u32_e32 v2, s8, v10
	v_mov_b64_e32 v[8:9], s[44:45]
	v_lshl_add_u64 v[6:7], s[6:7], 0, v[0:1]
	v_bfe_u32 v18, v12, 3, 7
	v_mad_i64_i32 v[2:3], s[6:7], v2, s5, v[8:9]
	v_or_b32_e32 v2, v2, v18
	v_lshlrev_b64 v[2:3], 7, v[2:3]
	v_lshl_add_u64 v[2:3], v[6:7], 0, v[2:3]
	s_barrier
	global_load_dwordx4 v[2:5], v[2:3], off
	v_readlane_b32 s10, v254, 3
	v_lshl_or_b32 v10, v10, 7, v18
	s_movk_i32 s11, 0x90
	v_add_u32_e32 v0, s10, v0
	v_mad_u64_u32 v[10:11], s[6:7], v10, s11, v[0:1]
	s_mul_i32 s0, s20, 0x410000
	s_or_b32 s4, s8, 1
	s_mul_hi_u32 s1, s8, 0x208000
	s_mul_hi_u32 s3, s4, 0x208000
	s_mul_i32 s4, s4, 0x208000
	s_mul_hi_u32 s2, s20, 0x410000
	v_lshlrev_b32_e32 v14, 3, v12
	v_lshrrev_b32_e32 v13, 5, v12
	v_bfe_u32 v57, v12, 1, 3
	v_bfe_u32 v56, v12, 5, 1
	v_bitop3_b32 v58, v56, v57, 2 bitop3:0x36
	v_lshlrev_b32_e32 v231, 4, v58
	v_cmp_lt_i32_e32 vcc, v248, v221
	s_mov_b32 s12, s45
	s_mov_b32 s13, s45
	s_mov_b32 s14, s45
	s_mov_b32 s15, s45
	s_mov_b32 s16, s45
	s_mov_b32 s17, s45
	s_mov_b32 s18, s45
	s_mov_b32 s19, s45
	v_mov_b32_e32 v216, 0x41b17218
	v_mov_b32_e32 v220, 0x3000
	v_mov_b32_e32 v196, 0x1000
	s_mov_b64 s[24:25], s[58:59]
	s_mov_b32 s22, 3
	v_mov_b32_e32 v238, 0
	v_mov_b32_e32 v114, 0
	v_add_u32_e32 v20, 0x200, v12
	v_ashrrev_i32_e32 v44, 10, v20
	v_bfe_u32 v45, v20, 3, 7
	v_add_u32_e32 v20, s8, v44
	v_mad_i64_i32 v[20:21], s[6:7], v20, s5, v[8:9]
	v_or_b32_e32 v20, v20, v45
	v_lshlrev_b64 v[20:21], 7, v[20:21]
	v_lshl_add_u64 v[20:21], v[6:7], 0, v[20:21]
	global_load_dwordx4 v[22:25], v[20:21], off
	v_lshl_or_b32 v34, v44, 7, v45
	v_mad_u64_u32 v[34:35], s[6:7], v34, s11, v[0:1]
	v_add_u32_e32 v20, 0x400, v12
	v_ashrrev_i32_e32 v44, 10, v20
	v_add_u32_e32 v20, s8, v44
	v_mad_i64_i32 v[20:21], s[6:7], v20, s5, v[8:9]
	v_or_b32_e32 v20, v20, v18
	v_lshlrev_b64 v[20:21], 7, v[20:21]
	v_lshl_add_u64 v[20:21], v[6:7], 0, v[20:21]
	global_load_dwordx4 v[26:29], v[20:21], off
	v_lshl_or_b32 v36, v44, 7, v18
	v_mad_u64_u32 v[36:37], s[6:7], v36, s11, v[0:1]
	v_add_u32_e32 v20, 0x600, v12
	v_ashrrev_i32_e32 v44, 10, v20
	v_bfe_u32 v45, v20, 3, 7
	v_add_u32_e32 v20, s8, v44
	v_mad_i64_i32 v[20:21], s[6:7], v20, s5, v[8:9]
	v_or_b32_e32 v20, v20, v45
	v_lshlrev_b64 v[20:21], 7, v[20:21]
	v_lshl_add_u64 v[20:21], v[6:7], 0, v[20:21]
	global_load_dwordx4 v[30:33], v[20:21], off
	v_lshl_or_b32 v38, v44, 7, v45
	v_mad_u64_u32 v[38:39], s[6:7], v38, s11, v[0:1]
	s_waitcnt vmcnt(3)
	ds_write_b128 v10, v[2:5]
	s_waitcnt vmcnt(2)
	ds_write_b128 v34, v[22:25]
	s_waitcnt vmcnt(1)
	ds_write_b128 v36, v[26:29]
	v_readlane_b32 s5, v251, 60
	s_add_u32 s6, s5, s0
	v_readlane_b32 s8, v251, 61
	s_addc_u32 s7, s8, s1
	s_add_u32 s4, s5, s4
	s_addc_u32 s5, s8, s3
	v_readlane_b32 s8, v251, 62
	v_readlane_b32 s9, v251, 63
	s_add_u32 s8, s8, s0
	s_addc_u32 s9, s9, s2
	s_movk_i32 s2, 0xffc0
	v_and_or_b32 v0, v14, s2, v15
	v_lshlrev_b64 v[50:51], 1, v[0:1]
	v_add_u32_e32 v0, 32, v17
	v_add_u32_e32 v223, 0x2000, v0
	v_readfirstlane_b32 s2, v0
	s_mov_b32 m0, s2
	v_readfirstlane_b32 s2, v223
	v_add_u32_e32 v224, 0x8000, v0
	v_lshl_add_u64 v[8:9], s[4:5], 0, v[50:51]
	v_add_u32_e32 v225, 0xa000, v0
	v_add_u32_e32 v226, 0x4000, v0
	v_and_b32_e32 v10, 31, v12
	v_add_u32_e32 v227, 0x6000, v0
	v_lshl_add_u32 v228, v10, 7, 32
	s_mov_b32 s4, s45
	s_mov_b32 s5, s45
	s_waitcnt vmcnt(0)
	ds_write_b128 v38, v[30:33]
	v_or_b32_e32 v2, v15, v16
	v_lshl_add_u64 v[6:7], s[6:7], 0, v[50:51]
	v_mov_b32_e32 v3, v1
	v_add_u32_e32 v4, 0x104000, v2
	global_load_lds_dwordx4 v[6:7], off
	s_mov_b32 m0, s2
	v_lshlrev_b64 v[52:53], 1, v[2:3]
	v_readfirstlane_b32 s2, v224
	v_mov_b32_e32 v5, v1
	global_load_lds_dwordx4 v[8:9], off
	v_lshl_add_u64 v[2:3], s[8:9], 0, v[52:53]
	s_mov_b32 m0, s2
	v_lshlrev_b64 v[54:55], 1, v[4:5]
	v_readfirstlane_b32 s2, v225
	global_load_lds_dwordx4 v[2:3], off
	v_lshl_add_u64 v[2:3], s[8:9], 0, v[54:55]
	s_mov_b32 m0, s2
	s_mov_b64 s[2:3], 0x2000
	global_load_lds_dwordx4 v[2:3], off
	v_lshl_add_u64 v[2:3], v[6:7], 0, s[2:3]
	v_lshl_add_u64 v[4:5], v[8:9], 0, s[2:3]
	v_readfirstlane_b32 s2, v226
	s_mov_b32 m0, s2
	v_readfirstlane_b32 s2, v227
	global_load_lds_dwordx4 v[2:3], off
	v_lshrrev_b32_e32 v3, 2, v12
	v_bfe_u32 v2, v12, 6, 1
	v_and_b32_e32 v3, 0xfffffe0, v3
	v_lshl_add_u32 v3, v2, 7, v3
	s_mov_b32 m0, s2
	v_or_b32_e32 v3, v3, v10
	v_lshl_add_u32 v62, v2, 13, v228
	v_bitop3_b32 v2, v13, v57, 1 bitop3:0x6c
	global_load_lds_dwordx4 v[4:5], off
	v_mul_lo_u32 v3, v3, s11
	v_lshlrev_b32_e32 v4, 4, v56
	v_lshlrev_b32_e32 v229, 4, v2
	v_add3_u32 v3, s10, v3, v4
	v_add_u32_e32 v230, v62, v229
	s_waitcnt vmcnt(0)
	s_waitcnt vmcnt(0) lgkmcnt(0)
	s_barrier
	ds_read_b128 v[162:165], v3
	ds_read_b128 v[166:169], v3 offset:32
	ds_read_b128 v[170:173], v3 offset:64
	ds_read_b128 v[174:177], v3 offset:96
	ds_read_b128 v[18:21], v230
	ds_read_b128 v[34:37], v230 offset:4096
	v_add_u32_e32 v232, v62, v231
	ds_read_b128 v[58:61], v232
	s_waitcnt lgkmcnt(2)
	v_mfma_f32_32x32x16_bf16 v[18:33], v[18:21], v[162:165], 0
	s_mov_b32 s6, s45
	s_mov_b32 s7, s45
	s_mov_b32 s8, s45
	s_mov_b32 s9, s45
	s_mov_b32 s10, s45
	s_mov_b32 s11, s45
	v_mov_b64_e32 v[2:3], s[4:5]
	s_waitcnt lgkmcnt(0)
	v_mfma_f32_32x32x16_bf16 v[18:33], v[58:61], v[166:169], v[18:33]
	ds_read_b128 v[58:61], v232 offset:4096
	v_mov_b64_e32 v[4:5], s[6:7]
	v_mov_b64_e32 v[6:7], s[8:9]
	v_mov_b64_e32 v[8:9], s[10:11]
	v_mov_b64_e32 v[10:11], s[12:13]
	v_mov_b64_e32 v[12:13], s[14:15]
	v_mov_b64_e32 v[14:15], s[16:17]
	v_mfma_f32_32x32x16_bf16 v[34:49], v[34:37], v[162:165], 0
	v_mov_b64_e32 v[16:17], s[18:19]
	v_readlane_b32 s4, v251, 2
	v_readlane_b32 s18, v251, 16
	v_readlane_b32 s19, v251, 17
	v_readlane_b32 s5, v251, 3
	v_readlane_b32 s6, v251, 4
	v_lshl_add_u64 v[180:181], s[18:19], 0, v[50:51]
	s_waitcnt lgkmcnt(0)
	v_mfma_f32_32x32x16_bf16 v[34:49], v[58:61], v[166:169], v[34:49]
	v_bitop3_b32 v58, v56, v57, 4 bitop3:0x36
	v_lshlrev_b32_e32 v233, 4, v58
	v_add_u32_e32 v234, v62, v233
	ds_read_b128 v[58:61], v234
	v_bitop3_b32 v56, v56, v57, 6 bitop3:0x36
	v_lshlrev_b32_e32 v235, 4, v56
	v_add_u32_e32 v236, v62, v235
	s_waitcnt lgkmcnt(0)
	v_mfma_f32_32x32x16_bf16 v[18:33], v[58:61], v[170:173], v[18:33]
	ds_read_b128 v[58:61], v234 offset:4096
	v_lshl_add_u64 v[182:183], s[18:19], 0, v[54:55]
	v_lshl_add_u64 v[184:185], s[18:19], 0, v[52:53]
	v_readlane_b32 s7, v251, 5
	v_readlane_b32 s8, v251, 6
	v_readlane_b32 s9, v251, 7
	v_readlane_b32 s10, v251, 8
	s_waitcnt lgkmcnt(0)
	v_mfma_f32_32x32x16_bf16 v[34:49], v[58:61], v[170:173], v[34:49]
	ds_read_b128 v[56:59], v236
	v_readlane_b32 s11, v251, 9
	v_readlane_b32 s12, v251, 10
	v_readlane_b32 s13, v251, 11
	v_readlane_b32 s14, v251, 12
	v_readlane_b32 s15, v251, 13
	v_readlane_b32 s16, v251, 14
	s_waitcnt lgkmcnt(0)
	v_mfma_f32_32x32x16_bf16 v[18:33], v[56:59], v[174:177], v[18:33]
	ds_read_b128 v[56:59], v236 offset:4096
	v_readlane_b32 s17, v251, 15
	s_waitcnt lgkmcnt(0)
	v_mfma_f32_32x32x16_bf16 v[34:49], v[56:59], v[174:177], v[34:49]
	s_nop 7
	v_max_f32_e32 v57, v19, v19
	v_max_f32_e32 v58, v20, v20
	v_max_f32_e32 v59, v21, v21
	s_nop 0
	v_max_f32_e32 v56, v35, v35
	v_max_f32_e32 v56, v57, v56
	v_max_f32_e32 v57, v36, v36
	v_max_f32_e32 v57, v58, v57
	v_max_f32_e32 v58, v37, v37
	v_max3_f32 v56, v18, v34, v56
	v_max_f32_e32 v58, v59, v58
	v_max3_f32 v56, v56, v57, v58
	v_max_f32_e32 v57, v38, v38
	v_max_f32_e32 v58, v22, v22
	v_max_f32_e32 v57, v58, v57
	v_max_f32_e32 v58, v39, v39
	v_max_f32_e32 v59, v23, v23
	v_max_f32_e32 v58, v59, v58
	v_max3_f32 v56, v56, v57, v58
	v_max_f32_e32 v57, v40, v40
	v_max_f32_e32 v58, v24, v24
	v_max_f32_e32 v57, v58, v57
	v_max_f32_e32 v58, v41, v41
	v_max_f32_e32 v59, v25, v25
	v_max_f32_e32 v58, v59, v58
	v_max3_f32 v56, v56, v57, v58
	v_max_f32_e32 v57, v42, v42
	v_max_f32_e32 v58, v26, v26
	v_max_f32_e32 v57, v58, v57
	v_max_f32_e32 v58, v43, v43
	v_max_f32_e32 v59, v27, v27
	v_max_f32_e32 v58, v59, v58
	v_max3_f32 v56, v56, v57, v58
	v_max_f32_e32 v57, v44, v44
	v_max_f32_e32 v58, v28, v28
	v_max_f32_e32 v57, v58, v57
	v_max_f32_e32 v58, v45, v45
	v_max_f32_e32 v59, v29, v29
	v_max_f32_e32 v58, v59, v58
	v_max3_f32 v56, v56, v57, v58
	v_max_f32_e32 v57, v46, v46
	v_max_f32_e32 v58, v30, v30
	v_max_f32_e32 v57, v58, v57
	v_max_f32_e32 v58, v47, v47
	v_max_f32_e32 v59, v31, v31
	v_max_f32_e32 v58, v59, v58
	v_max3_f32 v56, v56, v57, v58
	v_max_f32_e32 v57, v48, v48
	v_max_f32_e32 v58, v32, v32
	v_max_f32_e32 v57, v58, v57
	v_max_f32_e32 v58, v49, v49
	v_max_f32_e32 v59, v33, v33
	v_max_f32_e32 v58, v59, v58
	v_max3_f32 v56, v56, v57, v58
	v_cndmask_b32_e32 v57, v249, v248, vcc
	v_lshlrev_b32_e32 v222, 2, v57
	ds_bpermute_b32 v57, v222, v56
	s_waitcnt lgkmcnt(0)
	v_max_f32_e32 v57, v57, v57
	v_max_f32_e32 v237, v56, v57
	v_sub_f32_e32 v81, v49, v237
	v_sub_f32_e32 v80, v48, v237
	v_sub_f32_e32 v79, v47, v237
	v_sub_f32_e32 v78, v46, v237
	v_sub_f32_e32 v77, v45, v237
	v_sub_f32_e32 v76, v44, v237
	v_sub_f32_e32 v75, v43, v237
	v_sub_f32_e32 v74, v42, v237
	v_sub_f32_e32 v73, v41, v237
	v_sub_f32_e32 v72, v40, v237
	v_sub_f32_e32 v71, v39, v237
	v_sub_f32_e32 v70, v38, v237
	v_sub_f32_e32 v69, v37, v237
	v_sub_f32_e32 v68, v36, v237
	v_sub_f32_e32 v67, v35, v237
	v_sub_f32_e32 v66, v34, v237
	v_xor_b32_e32 v82, 0x80000000, v237
	v_sub_f32_e32 v113, v33, v237
	v_sub_f32_e32 v112, v32, v237
	v_sub_f32_e32 v111, v31, v237
	v_sub_f32_e32 v110, v30, v237
	v_sub_f32_e32 v109, v29, v237
	v_sub_f32_e32 v108, v28, v237
	v_sub_f32_e32 v107, v27, v237
	v_sub_f32_e32 v106, v26, v237
	v_sub_f32_e32 v105, v25, v237
	v_sub_f32_e32 v104, v24, v237
	v_sub_f32_e32 v103, v23, v237
	v_sub_f32_e32 v102, v22, v237
	v_sub_f32_e32 v101, v21, v237
	v_sub_f32_e32 v100, v20, v237
	v_sub_f32_e32 v99, v19, v237
	v_sub_f32_e32 v98, v18, v237
	v_mov_b64_e32 v[64:65], v[16:17]
	v_mov_b64_e32 v[48:49], v[16:17]
	v_mov_b64_e32 v[32:33], v[16:17]
	v_mov_b64_e32 v[62:63], v[14:15]
	v_mov_b64_e32 v[60:61], v[12:13]
	v_mov_b64_e32 v[58:59], v[10:11]
	v_mov_b64_e32 v[56:57], v[8:9]
	v_mov_b64_e32 v[54:55], v[6:7]
	v_mov_b64_e32 v[52:53], v[4:5]
	v_mov_b64_e32 v[50:51], v[2:3]
	v_mov_b64_e32 v[46:47], v[14:15]
	v_mov_b64_e32 v[44:45], v[12:13]
	v_mov_b64_e32 v[42:43], v[10:11]
	v_mov_b64_e32 v[40:41], v[8:9]
	v_mov_b64_e32 v[38:39], v[6:7]
	v_mov_b64_e32 v[36:37], v[4:5]
	v_mov_b64_e32 v[34:35], v[2:3]
	v_mov_b64_e32 v[30:31], v[14:15]
	v_mov_b64_e32 v[28:29], v[12:13]
	v_mov_b64_e32 v[26:27], v[10:11]
	v_mov_b64_e32 v[24:25], v[8:9]
	v_mov_b64_e32 v[22:23], v[6:7]
	v_mov_b64_e32 v[20:21], v[4:5]
	v_mov_b64_e32 v[18:19], v[2:3]
	v_mov_b32_e32 v83, v82
	v_mov_b32_e32 v84, v82
	v_mov_b32_e32 v85, v82
	v_mov_b32_e32 v86, v82
	v_mov_b32_e32 v87, v82
	v_mov_b32_e32 v88, v82
	v_mov_b32_e32 v89, v82
	v_mov_b32_e32 v90, v82
	v_mov_b32_e32 v91, v82
	v_mov_b32_e32 v92, v82
	v_mov_b32_e32 v93, v82
	v_mov_b32_e32 v94, v82
	v_mov_b32_e32 v95, v82
	v_mov_b32_e32 v96, v82
	v_mov_b32_e32 v97, v82
	s_branch .Latt_entry
